# final rmsnorm loop software-pipelined: next row's loads issued before the current row's reduce/scale/store
# speedup vs baseline: 1.0116x; 1.0116x over previous
; DI int otid() { int t = threadIdx.x; asm volatile("" : "+v"(t)); return t; }
; DI void rmsnorm_phase(const float* __restrict__ X, const float* __restrict__ g, bf16_t* __restrict__ H, float* __restrict__ OF) {
;   const int tid = otid(), lane = tid & 63;
;   const int gw = blockIdx.x * NWV + (tid >> 6), nw = gridDim.x * NWV;
;   for (int row = gw; row < T; row += nw) {
;     const float* xr = X + (size_t)row * D;
;     f32x4 v[8];
;     float ss = 0.f;
; #pragma unroll
;     for (int i = 0; i < 8; ++i) { v[i] = *(const f32x4*)(xr + lane * 4 + 256 * i); ss += v[i][0] * v[i][0] + v[i][1] * v[i][1] + v[i][2] * v[i][2] + v[i][3] * v[i][3]; }
;     ss = wave_sum(ss);
;     const float rstd = rsqrtf(ss * (1.f / D) + EPS);
; #pragma unroll
;     for (int i = 0; i < 8; ++i) {
;       const f32x4 gg = *(const f32x4*)(g + lane * 4 + 256 * i);
;       f32x4 o = v[i] * rstd * gg;
;       if (H) { u32x2 w; w.x = pk_bf16(o[0], o[1]); w.y = pk_bf16(o[2], o[3]); *(u32x2*)(H + (size_t)row * D + lane * 4 + 256 * i) = w; }
;       else *(f32x4*)(OF + (size_t)row * D + lane * 4 + 256 * i) = o;
;     }
;   }
; }
.LBB0_1707:
	s_or_b64 exec, exec, s[0:1]
	s_waitcnt lgkmcnt(0)
	s_barrier
	v_readlane_b32 s0, v252, 38
	v_ashrrev_i32_e32 v0, 6, v206
	s_nop 0
	v_add_u32_e32 v32, s0, v0
	s_movk_i32 s0, 0x4000
	v_cmp_gt_i32_e32 vcc, s0, v32
	s_and_saveexec_b64 s[0:1], vcc
	s_cbranch_execz .LBB0_1710
	v_lshlrev_b32_e32 v0, 4, v206
	v_and_b32_e32 v16, 0x3f0, v0
	v_mov_b32_e32 v17, 0
	v_lshl_add_u64 v[18:19], s[72:73], 0, v[16:17]
	s_movk_i32 s0, 0x1000
	v_add_co_u32_e32 v34, vcc, s0, v18
	global_load_dwordx4 v[0:3], v16, s[72:73]
	global_load_dwordx4 v[4:7], v16, s[72:73] offset:1024
	global_load_dwordx4 v[8:11], v16, s[72:73] offset:2048
	global_load_dwordx4 v[12:15], v16, s[72:73] offset:3072
	v_addc_co_u32_e32 v35, vcc, 0, v19, vcc
	global_load_dwordx4 v[16:19], v[34:35], off
	global_load_dwordx4 v[20:23], v[34:35], off offset:1024
	global_load_dwordx4 v[24:27], v[34:35], off offset:2048
	global_load_dwordx4 v[28:31], v[34:35], off offset:3072
	v_and_b32_e32 v33, 64, v198
	v_add_u32_e32 v33, 64, v33
	v_xor_b32_e32 v34, 32, v198
	v_cmp_lt_i32_e32 vcc, v34, v33
	s_mov_b64 s[0:1], 0x1000
	s_ashr_i32 s27, s26, 31
	v_cndmask_b32_e32 v34, v198, v34, vcc
	v_lshlrev_b32_e32 v36, 2, v34
	v_xor_b32_e32 v34, 16, v198
	v_cmp_lt_i32_e32 vcc, v34, v33
	s_lshl_b64 s[2:3], s[26:27], 13
	s_mov_b64 s[4:5], 0
	v_cndmask_b32_e32 v34, v198, v34, vcc
	v_lshlrev_b32_e32 v37, 2, v34
	v_xor_b32_e32 v34, 8, v198
	v_cmp_lt_i32_e32 vcc, v34, v33
	s_mov_b32 s6, 0x800000
	s_movk_i32 s7, 0x3fff
	v_cndmask_b32_e32 v34, v198, v34, vcc
	v_lshlrev_b32_e32 v38, 2, v34
	v_xor_b32_e32 v34, 4, v198
	v_cmp_lt_i32_e32 vcc, v34, v33
	s_nop 1
	v_cndmask_b32_e32 v34, v198, v34, vcc
	v_lshlrev_b32_e32 v39, 2, v34
	v_xor_b32_e32 v34, 2, v198
	v_cmp_lt_i32_e32 vcc, v34, v33
	s_nop 1
	v_cndmask_b32_e32 v34, v198, v34, vcc
	v_lshlrev_b32_e32 v40, 2, v34
	v_xor_b32_e32 v34, 1, v198
	v_cmp_lt_i32_e32 vcc, v34, v33
	s_nop 1
	v_cndmask_b32_e32 v33, v198, v34, vcc
	v_lshlrev_b32_e32 v41, 2, v33
	v_ashrrev_i32_e32 v33, 31, v32
	v_lshlrev_b64 v[34:35], 13, v[32:33]
	v_and_b32_e32 v33, 63, v206
	v_lshl_or_b32 v34, v33, 4, v34
	v_lshl_add_u64 v[34:35], s[20:21], 0, v[34:35]
	v_lshl_add_u64 v[34:35], v[34:35], 0, s[0:1]
	v_mov_b32_e32 v33, 0x358637bd
	global_load_dwordx4 v[100:103], v[34:35], off offset:-4096
	global_load_dwordx4 v[104:107], v[34:35], off offset:-3072
	global_load_dwordx4 v[108:111], v[34:35], off offset:-2048
	global_load_dwordx4 v[112:115], v[34:35], off offset:-1024
	global_load_dwordx4 v[116:119], v[34:35], off
	global_load_dwordx4 v[120:123], v[34:35], off offset:1024
	global_load_dwordx4 v[124:127], v[34:35], off offset:2048
	global_load_dwordx4 v[128:131], v[34:35], off offset:3072
	s_waitcnt vmcnt(0)
	s_branch .Lrn12_body
.LBB0_1709:
	s_waitcnt vmcnt(8)
; DI int otid() { int t = threadIdx.x; asm volatile("" : "+v"(t)); return t; }
; DI void rmsnorm_phase(const float* __restrict__ X, const float* __restrict__ g, bf16_t* __restrict__ H, float* __restrict__ OF) {
;   const int tid = otid(), lane = tid & 63;
;   const int gw = blockIdx.x * NWV + (tid >> 6), nw = gridDim.x * NWV;
;   for (int row = gw; row < T; row += nw) {
;     const float* xr = X + (size_t)row * D;
;     f32x4 v[8];
;     float ss = 0.f;
; #pragma unroll
;     for (int i = 0; i < 8; ++i) { v[i] = *(const f32x4*)(xr + lane * 4 + 256 * i); ss += v[i][0] * v[i][0] + v[i][1] * v[i][1] + v[i][2] * v[i][2] + v[i][3] * v[i][3]; }
;     ss = wave_sum(ss);
;     const float rstd = rsqrtf(ss * (1.f / D) + EPS);
; #pragma unroll
;     for (int i = 0; i < 8; ++i) {
;       const f32x4 gg = *(const f32x4*)(g + lane * 4 + 256 * i);
;       f32x4 o = v[i] * rstd * gg;
;       if (H) { u32x2 w; w.x = pk_bf16(o[0], o[1]); w.y = pk_bf16(o[2], o[3]); *(u32x2*)(H + (size_t)row * D + lane * 4 + 256 * i) = w; }
;       else *(f32x4*)(OF + (size_t)row * D + lane * 4 + 256 * i) = o;
;     }
;   }
; }
.Lrn12_body:
	v_mov_b64_e32 v[42:43], v[100:101]
	v_mov_b64_e32 v[44:45], v[102:103]
	v_mov_b64_e32 v[46:47], v[104:105]
	v_mov_b64_e32 v[48:49], v[106:107]
	v_mov_b64_e32 v[50:51], v[108:109]
	v_mov_b64_e32 v[52:53], v[110:111]
	v_mov_b64_e32 v[54:55], v[112:113]
	v_mov_b64_e32 v[56:57], v[114:115]
	v_mov_b64_e32 v[58:59], v[116:117]
	v_mov_b64_e32 v[60:61], v[118:119]
	v_mov_b64_e32 v[62:63], v[120:121]
	v_mov_b64_e32 v[64:65], v[122:123]
	v_mov_b64_e32 v[66:67], v[124:125]
	v_mov_b64_e32 v[68:69], v[126:127]
	v_mov_b64_e32 v[70:71], v[128:129]
	v_mov_b64_e32 v[72:73], v[130:131]
	v_add_u32_e32 v32, s26, v32
	v_cmp_lt_i32_e64 s[0:1], s7, v32
	s_or_b64 s[4:5], s[0:1], s[4:5]
	v_mov_b64_e32 v[96:97], v[34:35]
	v_lshl_add_u64 v[98:99], v[34:35], 0, s[2:3]
	v_cndmask_b32_e64 v34, v98, v34, s[0:1]
	v_cndmask_b32_e64 v35, v99, v35, s[0:1]
	global_load_dwordx4 v[100:103], v[34:35], off offset:-4096
	global_load_dwordx4 v[104:107], v[34:35], off offset:-3072
	global_load_dwordx4 v[108:111], v[34:35], off offset:-2048
	global_load_dwordx4 v[112:115], v[34:35], off offset:-1024
	global_load_dwordx4 v[116:119], v[34:35], off
	global_load_dwordx4 v[120:123], v[34:35], off offset:1024
	global_load_dwordx4 v[124:127], v[34:35], off offset:2048
	global_load_dwordx4 v[128:131], v[34:35], off offset:3072
	v_mul_f32_e32 v90, v43, v43
	v_mul_f32_e32 v91, v47, v47
	v_mul_f32_e32 v92, v51, v51
	v_fmac_f32_e32 v90, v42, v42
	v_mov_b32_e32 v76, v59
	v_mov_b32_e32 v77, v63
	v_fmac_f32_e32 v91, v46, v46
	v_mul_f32_e32 v93, v55, v55
	v_mov_b32_e32 v74, v58
	v_mov_b32_e32 v75, v62
	v_fmac_f32_e32 v92, v50, v50
	v_pk_mul_f32 v[76:77], v[76:77], v[76:77]
	v_fmac_f32_e32 v90, v44, v44
	v_fmac_f32_e32 v91, v48, v48
	v_mov_b32_e32 v78, v60
	v_mov_b32_e32 v79, v64
	v_fmac_f32_e32 v93, v54, v54
	v_fmac_f32_e32 v92, v52, v52
	v_pk_fma_f32 v[74:75], v[74:75], v[74:75], v[76:77]
	v_fmac_f32_e32 v90, v45, v45
	v_fmac_f32_e32 v91, v49, v49
	v_mov_b32_e32 v84, v67
	v_mov_b32_e32 v85, v71
	v_fmac_f32_e32 v93, v56, v56
	v_fmac_f32_e32 v92, v53, v53
	v_pk_fma_f32 v[74:75], v[78:79], v[78:79], v[74:75]
	v_add_f32_e32 v78, v90, v91
	v_mov_b32_e32 v80, v61
	v_mov_b32_e32 v81, v65
	v_mov_b32_e32 v82, v66
	v_mov_b32_e32 v83, v70
	v_pk_mul_f32 v[84:85], v[84:85], v[84:85]
	v_fmac_f32_e32 v93, v57, v57
	v_add_f32_e32 v78, v78, v92
	v_mov_b32_e32 v86, v68
	v_mov_b32_e32 v87, v72
	v_pk_fma_f32 v[76:77], v[82:83], v[82:83], v[84:85]
	v_pk_fma_f32 v[74:75], v[80:81], v[80:81], v[74:75]
	v_add_f32_e32 v78, v78, v93
	v_mov_b32_e32 v88, v69
	v_mov_b32_e32 v89, v73
	v_pk_fma_f32 v[76:77], v[86:87], v[86:87], v[76:77]
	v_add_f32_e32 v74, v78, v74
	v_pk_fma_f32 v[76:77], v[88:89], v[88:89], v[76:77]
	v_add_f32_e32 v74, v74, v75
	v_add_f32_e32 v74, v74, v76
	v_add_f32_e32 v74, v74, v77
	ds_bpermute_b32 v75, v36, v74
	s_waitcnt lgkmcnt(0)
	v_add_f32_e32 v74, v74, v75
	ds_bpermute_b32 v75, v37, v74
	s_waitcnt lgkmcnt(0)
	v_add_f32_e32 v74, v74, v75
	ds_bpermute_b32 v75, v38, v74
	s_waitcnt lgkmcnt(0)
	v_add_f32_e32 v74, v74, v75
	ds_bpermute_b32 v75, v39, v74
	s_waitcnt lgkmcnt(0)
	v_add_f32_e32 v74, v74, v75
	ds_bpermute_b32 v75, v40, v74
	s_waitcnt lgkmcnt(0)
	v_add_f32_e32 v74, v74, v75
	ds_bpermute_b32 v75, v41, v74
	s_waitcnt lgkmcnt(0)
	v_add_f32_e32 v74, v74, v75
	v_fmamk_f32 v74, v74, 0x3a000000, v33
	v_mul_f32_e32 v75, 0x4b800000, v74
	v_cmp_gt_f32_e32 vcc, s6, v74
	s_nop 1
	v_cndmask_b32_e32 v74, v74, v75, vcc
	v_rsq_f32_e32 v74, v74
	s_nop 0
	v_mul_f32_e32 v75, 0x45800000, v74
	v_cndmask_b32_e32 v74, v74, v75, vcc
	v_pk_mul_f32 v[42:43], v[42:43], v[74:75] op_sel_hi:[1,0]
	v_pk_mul_f32 v[44:45], v[44:45], v[74:75] op_sel_hi:[1,0]
	v_pk_mul_f32 v[46:47], v[46:47], v[74:75] op_sel_hi:[1,0]
	v_pk_mul_f32 v[48:49], v[48:49], v[74:75] op_sel_hi:[1,0]
	v_pk_mul_f32 v[50:51], v[50:51], v[74:75] op_sel_hi:[1,0]
	v_pk_mul_f32 v[52:53], v[52:53], v[74:75] op_sel_hi:[1,0]
	v_pk_mul_f32 v[54:55], v[54:55], v[74:75] op_sel_hi:[1,0]
	v_pk_mul_f32 v[56:57], v[56:57], v[74:75] op_sel_hi:[1,0]
	v_pk_mul_f32 v[58:59], v[58:59], v[74:75] op_sel_hi:[1,0]
	v_pk_mul_f32 v[60:61], v[60:61], v[74:75] op_sel_hi:[1,0]
	v_pk_mul_f32 v[62:63], v[62:63], v[74:75] op_sel_hi:[1,0]
	v_pk_mul_f32 v[64:65], v[64:65], v[74:75] op_sel_hi:[1,0]
	v_pk_mul_f32 v[66:67], v[66:67], v[74:75] op_sel_hi:[1,0]
	v_pk_mul_f32 v[68:69], v[68:69], v[74:75] op_sel_hi:[1,0]
	v_pk_mul_f32 v[70:71], v[70:71], v[74:75] op_sel_hi:[1,0]
	v_pk_mul_f32 v[72:73], v[72:73], v[74:75] op_sel_hi:[1,0]
	v_pk_mul_f32 v[44:45], v[2:3], v[44:45]
	v_pk_mul_f32 v[42:43], v[0:1], v[42:43]
	v_pk_mul_f32 v[48:49], v[6:7], v[48:49]
	v_pk_mul_f32 v[46:47], v[4:5], v[46:47]
	v_pk_mul_f32 v[52:53], v[10:11], v[52:53]
	v_pk_mul_f32 v[50:51], v[8:9], v[50:51]
	v_pk_mul_f32 v[56:57], v[14:15], v[56:57]
	v_pk_mul_f32 v[54:55], v[12:13], v[54:55]
	v_pk_mul_f32 v[60:61], v[18:19], v[60:61]
	v_pk_mul_f32 v[58:59], v[16:17], v[58:59]
	v_pk_mul_f32 v[64:65], v[22:23], v[64:65]
	v_pk_mul_f32 v[62:63], v[20:21], v[62:63]
	v_pk_mul_f32 v[68:69], v[26:27], v[68:69]
	v_pk_mul_f32 v[66:67], v[24:25], v[66:67]
	v_pk_mul_f32 v[72:73], v[30:31], v[72:73]
	v_pk_mul_f32 v[70:71], v[28:29], v[70:71]
	global_store_dwordx4 v[96:97], v[42:45], off offset:-4096
	global_store_dwordx4 v[96:97], v[46:49], off offset:-3072
	global_store_dwordx4 v[96:97], v[50:53], off offset:-2048
	global_store_dwordx4 v[96:97], v[54:57], off offset:-1024
	global_store_dwordx4 v[96:97], v[58:61], off
	global_store_dwordx4 v[96:97], v[62:65], off offset:1024
	global_store_dwordx4 v[96:97], v[66:69], off offset:2048
	global_store_dwordx4 v[96:97], v[70:73], off offset:3072
	s_andn2_b64 exec, exec, s[4:5]
	s_cbranch_execnz .LBB0_1709
